# C5 + in-projection GEMM plain tiles: wave owns 64 contiguous output columns (B fragment LDS bases remapped), the two 64B stores of a row fill one 128B line back to back
# speedup vs baseline: 1.0163x; 1.0125x over previous
; #define PG8_STAGE(bufoff, gbase, voff) do { _Pragma("unroll") for (int _i = 0; _i < 2; ++_i) \
;         __builtin_amdgcn_global_load_lds((const unsigned*)((const char*)(gbase) + (voff)[_i]), (PG8_LAS unsigned*)(lds + (bufoff) + ldsw + _i * 8192), 16, 0, 0); } while (0)
; #define PG8_LDA(dst, b, h) do { _Pragma("unroll") for (int m = 0; m < 4; ++m) _Pragma("unroll") for (int k = 0; k < 2; ++k) dst[m][k] = *(const PG8_LAS bf16x8*)(lds + PG8_SA(b, h) + aoff + m * 2048 + k * 1024); } while (0)
; #define PG8_LDB(dst, b, h) do { _Pragma("unroll") for (int n = 0; n < 2; ++n) _Pragma("unroll") for (int k = 0; k < 2; ++k) dst[n][k] = *(const PG8_LAS bf16x8*)(lds + PG8_SB(b, h) + boff + n * 2048 + k * 1024); } while (0)
; #define PG8_MMA(ai, bj, At, Bt) do { __builtin_amdgcn_s_setprio(1); _Pragma("unroll") for (int m = 0; m < 4; ++m) _Pragma("unroll") for (int n = 0; n < 2; ++n) _Pragma("unroll") for (int k = 0; k < 2; ++k) \
;         acc[ai][bj][m][n] = __builtin_amdgcn_mfma_f32_16x16x32_bf16(Bt[n][k], At[m][k], acc[ai][bj][m][n], 0, 0, 0); __builtin_amdgcn_s_setprio(0); } while (0)
; #define PG8_WAIT_V(n) asm volatile("s_waitcnt vmcnt(" #n ")" ::: "memory")
; #define PG8_WAIT_L(n) asm volatile("s_waitcnt lgkmcnt(" #n ")" ::: "memory")
; #define PG8_BAR __builtin_amdgcn_s_barrier()
; #define PG8_SCHED __builtin_amdgcn_sched_barrier(0)
; template <class Epi, class Sched, bool ALIGN_EPI = false, bool SP2 = false>
; __device__ __forceinline__ void gemm_phase(PG8_LAS unsigned char* lds, const Gemm g, const Sched& S, const Epi& E) {
;     ...
;     f32x4 acc[2][2][4][2];
; #pragma unroll
;     for (int a = 0; a < 2; ++a)
; #pragma unroll
;         for (int b = 0; b < 2; ++b)
; #pragma unroll
;             for (int m = 0; m < 4; ++m)
; #pragma unroll
;                 for (int n = 0; n < 2; ++n) acc[a][b][m][n] = (f32x4){0.f, 0.f, 0.f, 0.f};
;     ...
;             PG8_LDB(B0, 0, 0); PG8_LDB(B1, 0, 1); PG8_SCHED; PG8_LDA(At, 0, 0); PG8_STAGE(PG8_SA(1, 1), a1 + hstep, voffA);
;             PG8_WAIT_V(8); PG8_WAIT_L(0); PG8_BAR; PG8_MMA(0, 0, At, B0); PG8_MMA(0, 1, At, B1); PG8_BAR; PG8_SCHED;
.LBB0_187:
	s_and_b32 s32, s6, -4
	s_cmp_lg_u32 s32, 8
	s_cselect_b32 s32, 1, 0
	s_and_b32 vcc_lo, s6, -8
	s_cmp_lg_u32 vcc_lo, 24
	s_cselect_b32 vcc_lo, s32, 0
	s_cmp_lg_u32 s6, 56
	s_cselect_b32 s32, vcc_lo, 0
	s_and_b32 vcc_lo, s0, 3
	s_lshl_b32 vcc_lo, vcc_lo, 12
	s_mul_i32 vcc_lo, vcc_lo, s32
	s_mulk_i32 s32, 0x3000
	s_sub_i32 s32, vcc_lo, s32
	v_add_u32_e32 v177, vcc_lo, v159
	v_add_u32_e32 v244, s32, v159
	v_add_u32_e32 v174, s82, v177
	v_add_u32_e32 v175, s83, v244
	s_ashr_i32 s35, s34, 31
	s_lshl_b64 s[36:37], s[34:35], 20
	s_add_u32 s36, s92, s36
	s_addc_u32 s37, s93, s37
	s_and_b64 s[38:39], s[4:5], exec
	s_cselect_b32 s1, s37, s41
	s_cselect_b32 s3, s36, s40
	s_ashr_i32 s31, s30, 31
	s_lshl_b64 s[38:39], s[30:31], 20
	s_add_u32 s38, s47, s38
	s_addc_u32 s39, s48, s39
	s_and_b64 s[44:45], s[4:5], exec
	s_cselect_b32 s7, s39, s43
	s_cselect_b32 s10, s38, s42
	s_add_u32 s40, s40, 0x80080
	s_addc_u32 s41, s41, 0
	s_add_u32 s13, s42, 0x100
	s_waitcnt lgkmcnt(0)
	v_mov_b32_e32 v66, 0
	s_addc_u32 s31, s43, 0
	s_mov_b32 s33, -2
	v_mov_b32_e32 v67, v66
	v_mov_b32_e32 v68, v66
	v_mov_b32_e32 v69, v66
	v_mov_b32_e32 v74, v66
	v_mov_b32_e32 v75, v66
	v_mov_b32_e32 v76, v66
	v_mov_b32_e32 v77, v66
	v_mov_b32_e32 v70, v66
	v_mov_b32_e32 v71, v66
	v_mov_b32_e32 v72, v66
	v_mov_b32_e32 v73, v66
	v_mov_b32_e32 v78, v66
	v_mov_b32_e32 v79, v66
	v_mov_b32_e32 v80, v66
	v_mov_b32_e32 v81, v66
	v_mov_b32_e32 v82, v66
	v_mov_b32_e32 v83, v66
	v_mov_b32_e32 v84, v66
	v_mov_b32_e32 v85, v66
	v_mov_b32_e32 v86, v66
	v_mov_b32_e32 v87, v66
	v_mov_b32_e32 v88, v66
	v_mov_b32_e32 v89, v66
	v_mov_b32_e32 v90, v66
	v_mov_b32_e32 v91, v66
	v_mov_b32_e32 v92, v66
	v_mov_b32_e32 v93, v66
	v_mov_b32_e32 v94, v66
	v_mov_b32_e32 v95, v66
	v_mov_b32_e32 v96, v66
	v_mov_b32_e32 v97, v66
	v_mov_b32_e32 v0, v66
	v_mov_b32_e32 v1, v66
	v_mov_b32_e32 v2, v66
	v_mov_b32_e32 v3, v66
	v_mov_b32_e32 v4, v66
	v_mov_b32_e32 v5, v66
	v_mov_b32_e32 v6, v66
	v_mov_b32_e32 v7, v66
	v_mov_b32_e32 v8, v66
	v_mov_b32_e32 v9, v66
	v_mov_b32_e32 v10, v66
	v_mov_b32_e32 v11, v66
	v_mov_b32_e32 v12, v66
	v_mov_b32_e32 v13, v66
	v_mov_b32_e32 v14, v66
	v_mov_b32_e32 v15, v66
	v_mov_b32_e32 v16, v66
	v_mov_b32_e32 v17, v66
	v_mov_b32_e32 v18, v66
	v_mov_b32_e32 v19, v66
	v_mov_b32_e32 v20, v66
	v_mov_b32_e32 v21, v66
	v_mov_b32_e32 v22, v66
	v_mov_b32_e32 v23, v66
	v_mov_b32_e32 v24, v66
	v_mov_b32_e32 v25, v66
	v_mov_b32_e32 v26, v66
	v_mov_b32_e32 v27, v66
	v_mov_b32_e32 v28, v66
	v_mov_b32_e32 v29, v66
	v_mov_b32_e32 v30, v66
	v_mov_b32_e32 v31, v66
	v_mov_b32_e32 v98, v66
	v_mov_b32_e32 v99, v66
	v_mov_b32_e32 v100, v66
	v_mov_b32_e32 v101, v66
	v_mov_b32_e32 v102, v66
	v_mov_b32_e32 v103, v66
	v_mov_b32_e32 v104, v66
	v_mov_b32_e32 v105, v66
	v_mov_b32_e32 v106, v66
	v_mov_b32_e32 v107, v66
	v_mov_b32_e32 v108, v66
	v_mov_b32_e32 v109, v66
	v_mov_b32_e32 v110, v66
	v_mov_b32_e32 v111, v66
	v_mov_b32_e32 v112, v66
	v_mov_b32_e32 v113, v66
	v_mov_b32_e32 v114, v66
	v_mov_b32_e32 v115, v66
	v_mov_b32_e32 v116, v66
	v_mov_b32_e32 v117, v66
	v_mov_b32_e32 v118, v66
	v_mov_b32_e32 v119, v66
	v_mov_b32_e32 v120, v66
	v_mov_b32_e32 v121, v66
	v_mov_b32_e32 v122, v66
	v_mov_b32_e32 v123, v66
	v_mov_b32_e32 v124, v66
	v_mov_b32_e32 v125, v66
	v_mov_b32_e32 v126, v66
	v_mov_b32_e32 v127, v66
	v_mov_b32_e32 v128, v66
	v_mov_b32_e32 v129, v66
	v_mov_b32_e32 v32, v66
	v_mov_b32_e32 v33, v66
	v_mov_b32_e32 v34, v66
	v_mov_b32_e32 v35, v66
	v_mov_b32_e32 v36, v66
	v_mov_b32_e32 v37, v66
	v_mov_b32_e32 v38, v66
	v_mov_b32_e32 v39, v66
	v_mov_b32_e32 v40, v66
	v_mov_b32_e32 v41, v66
	v_mov_b32_e32 v42, v66
	v_mov_b32_e32 v43, v66
	v_mov_b32_e32 v44, v66
	v_mov_b32_e32 v45, v66
	v_mov_b32_e32 v46, v66
	v_mov_b32_e32 v47, v66
	v_mov_b32_e32 v48, v66
	v_mov_b32_e32 v49, v66
	v_mov_b32_e32 v50, v66
	v_mov_b32_e32 v51, v66
	v_mov_b32_e32 v52, v66
	v_mov_b32_e32 v53, v66
	v_mov_b32_e32 v54, v66
	v_mov_b32_e32 v55, v66
	v_mov_b32_e32 v56, v66
	v_mov_b32_e32 v57, v66
	v_mov_b32_e32 v58, v66
	v_mov_b32_e32 v59, v66
	v_mov_b32_e32 v60, v66
	v_mov_b32_e32 v61, v66
	v_mov_b32_e32 v62, v66
	v_mov_b32_e32 v63, v66
.LBB0_188:
	ds_read_b128 v[130:133], v174
	ds_read_b128 v[178:181], v174 offset:1024
	ds_read_b128 v[182:185], v174 offset:2048
	ds_read_b128 v[186:189], v174 offset:3072
	ds_read_b128 v[190:193], v175
	ds_read_b128 v[194:197], v175 offset:1024
	ds_read_b128 v[198:201], v175 offset:2048
	ds_read_b128 v[202:205], v175 offset:3072
	s_add_u32 s35, s40, 0xfff80080
	s_addc_u32 s42, s41, -1
	s_cmp_eq_u32 s33, 28
	s_cselect_b32 s45, s1, s42
	s_cselect_b32 s44, s3, s35
	s_cselect_b32 s43, s7, s31
	s_cselect_b32 s42, s10, s13
	v_lshl_add_u64 v[64:65], s[40:41], 0, v[148:149]
	s_add_i32 m0, s50, 0xc000
	ds_read_b128 v[206:209], v176
	ds_read_b128 v[210:213], v176 offset:1024
	ds_read_b128 v[214:217], v176 offset:2048
	ds_read_b128 v[218:221], v176 offset:3072
	ds_read_b128 v[222:225], v176 offset:4096
	ds_read_b128 v[226:229], v176 offset:5120
	ds_read_b128 v[230:233], v176 offset:6144
	ds_read_b128 v[234:237], v176 offset:7168
	global_load_lds_dwordx4 v[64:65], off
	v_lshl_add_u64 v[64:65], s[40:41], 0, v[150:151]
	s_add_i32 m0, s50, 0xe000
	s_nop 0
	global_load_lds_dwordx4 v[64:65], off
	s_waitcnt vmcnt(8)
	s_waitcnt lgkmcnt(0)
	s_barrier
; #define PG8_STAGE(bufoff, gbase, voff) do { _Pragma("unroll") for (int _i = 0; _i < 2; ++_i) \
;         __builtin_amdgcn_global_load_lds((const unsigned*)((const char*)(gbase) + (voff)[_i]), (PG8_LAS unsigned*)(lds + (bufoff) + ldsw + _i * 8192), 16, 0, 0); } while (0)
; #define PG8_LDA(dst, b, h) do { _Pragma("unroll") for (int m = 0; m < 4; ++m) _Pragma("unroll") for (int k = 0; k < 2; ++k) dst[m][k] = *(const PG8_LAS bf16x8*)(lds + PG8_SA(b, h) + aoff + m * 2048 + k * 1024); } while (0)
; #define PG8_MMA(ai, bj, At, Bt) do { __builtin_amdgcn_s_setprio(1); _Pragma("unroll") for (int m = 0; m < 4; ++m) _Pragma("unroll") for (int n = 0; n < 2; ++n) _Pragma("unroll") for (int k = 0; k < 2; ++k) \
;         acc[ai][bj][m][n] = __builtin_amdgcn_mfma_f32_16x16x32_bf16(Bt[n][k], At[m][k], acc[ai][bj][m][n], 0, 0, 0); __builtin_amdgcn_s_setprio(0); } while (0)
; #define PG8_WAIT_V(n) asm volatile("s_waitcnt vmcnt(" #n ")" ::: "memory")
; #define PG8_WAIT_L(n) asm volatile("s_waitcnt lgkmcnt(" #n ")" ::: "memory")
; #define PG8_BAR __builtin_amdgcn_s_barrier()
; #define PG8_SCHED __builtin_amdgcn_sched_barrier(0)
; template <class Epi, class Sched, bool ALIGN_EPI = false, bool SP2 = false>
; __device__ __forceinline__ void gemm_phase(PG8_LAS unsigned char* lds, const Gemm g, const Sched& S, const Epi& E) {
;     ...
;             PG8_WAIT_V(8); PG8_WAIT_L(0); PG8_BAR; PG8_MMA(0, 0, At, B0); PG8_MMA(0, 1, At, B1); PG8_BAR; PG8_SCHED;
;             PG8_LDA(At, 0, 1); PG8_STAGE(PG8_SB(0, 0), b2, voffB); PG8_STAGE(PG8_SB(0, 1), b2 + hstep, voffB); PG8_STAGE(PG8_SA(0, 0), a2, voffA);
;             PG8_WAIT_V(8); PG8_WAIT_L(0); PG8_BAR; PG8_MMA(1, 0, At, B0); PG8_MMA(1, 1, At, B1); PG8_BAR; PG8_SCHED;
	s_setprio 1
	s_waitcnt lgkmcnt(0)
	v_mfma_f32_16x16x32_bf16 v[60:63], v[130:133], v[206:209], v[60:63]
	v_mfma_f32_16x16x32_bf16 v[56:59], v[182:185], v[206:209], v[56:59]
	v_mfma_f32_16x16x32_bf16 v[52:55], v[130:133], v[214:217], v[52:55]
	v_mfma_f32_16x16x32_bf16 v[48:51], v[182:185], v[214:217], v[48:51]
	v_mfma_f32_16x16x32_bf16 v[44:47], v[130:133], v[222:225], v[44:47]
	v_mfma_f32_16x16x32_bf16 v[40:43], v[182:185], v[222:225], v[40:43]
	v_mfma_f32_16x16x32_bf16 v[36:39], v[130:133], v[230:233], v[36:39]
	v_mfma_f32_16x16x32_bf16 v[32:35], v[182:185], v[230:233], v[32:35]
	v_mfma_f32_16x16x32_bf16 v[60:63], v[178:181], v[210:213], v[60:63]
	v_mfma_f32_16x16x32_bf16 v[56:59], v[186:189], v[210:213], v[56:59]
	v_mfma_f32_16x16x32_bf16 v[52:55], v[178:181], v[218:221], v[52:55]
	v_mfma_f32_16x16x32_bf16 v[48:51], v[186:189], v[218:221], v[48:51]
	v_mfma_f32_16x16x32_bf16 v[44:47], v[178:181], v[226:229], v[44:47]
	v_mfma_f32_16x16x32_bf16 v[40:43], v[186:189], v[226:229], v[40:43]
	v_mfma_f32_16x16x32_bf16 v[36:39], v[178:181], v[234:237], v[36:39]
	v_mfma_f32_16x16x32_bf16 v[32:35], v[186:189], v[234:237], v[32:35]
	s_setprio 0
	s_setprio 1
	v_mfma_f32_16x16x32_bf16 v[126:129], v[190:193], v[206:209], v[126:129]
	v_mfma_f32_16x16x32_bf16 v[122:125], v[198:201], v[206:209], v[122:125]
	v_mfma_f32_16x16x32_bf16 v[118:121], v[190:193], v[214:217], v[118:121]
	v_mfma_f32_16x16x32_bf16 v[114:117], v[198:201], v[214:217], v[114:117]
	v_mfma_f32_16x16x32_bf16 v[110:113], v[190:193], v[222:225], v[110:113]
	v_mfma_f32_16x16x32_bf16 v[106:109], v[198:201], v[222:225], v[106:109]
	v_mfma_f32_16x16x32_bf16 v[102:105], v[190:193], v[230:233], v[102:105]
	v_mfma_f32_16x16x32_bf16 v[98:101], v[198:201], v[230:233], v[98:101]
	v_mfma_f32_16x16x32_bf16 v[126:129], v[194:197], v[210:213], v[126:129]
	v_mfma_f32_16x16x32_bf16 v[122:125], v[202:205], v[210:213], v[122:125]
	v_mfma_f32_16x16x32_bf16 v[118:121], v[194:197], v[218:221], v[118:121]
	v_mfma_f32_16x16x32_bf16 v[114:117], v[202:205], v[218:221], v[114:117]
	v_mfma_f32_16x16x32_bf16 v[110:113], v[194:197], v[226:229], v[110:113]
	v_mfma_f32_16x16x32_bf16 v[106:109], v[202:205], v[226:229], v[106:109]
	v_mfma_f32_16x16x32_bf16 v[102:105], v[194:197], v[234:237], v[102:105]
	v_mfma_f32_16x16x32_bf16 v[98:101], v[202:205], v[234:237], v[98:101]
	s_setprio 0
	s_barrier
	s_add_i32 s35, s82, s49
	v_lshl_add_u64 v[156:157], s[42:43], 0, v[136:137]
	s_mov_b32 m0, s35
	ds_read_b128 v[206:209], v176 offset:16384
	ds_read_b128 v[210:213], v176 offset:17408
	ds_read_b128 v[214:217], v176 offset:18432
	ds_read_b128 v[218:221], v176 offset:19456
	ds_read_b128 v[222:225], v176 offset:20480
	ds_read_b128 v[226:229], v176 offset:21504
	ds_read_b128 v[230:233], v176 offset:22528
	ds_read_b128 v[234:237], v176 offset:23552
	global_load_lds_dwordx4 v[156:157], off
	s_add_i32 m0, s35, 0x2000
	s_add_u32 s56, s42, 0x80000
	v_lshl_add_u64 v[238:239], s[42:43], 0, v[140:141]
	s_addc_u32 s57, s43, 0
	s_add_i32 s35, s83, s49
	global_load_lds_dwordx4 v[238:239], off
	v_lshl_add_u64 v[64:65], s[56:57], 0, v[136:137]
	s_mov_b32 m0, s35
	v_lshl_add_u64 v[240:241], s[44:45], 0, v[134:135]
	global_load_lds_dwordx4 v[64:65], off
	v_lshl_add_u64 v[64:65], s[56:57], 0, v[140:141]
	s_add_i32 m0, s35, 0x2000
	v_lshl_add_u64 v[242:243], s[44:45], 0, v[138:139]
	global_load_lds_dwordx4 v[64:65], off
	s_mov_b32 m0, s50
	s_nop 0
	global_load_lds_dwordx4 v[240:241], off
	s_mov_b32 m0, s51
	s_nop 0
	global_load_lds_dwordx4 v[242:243], off
	s_waitcnt vmcnt(8)
	s_waitcnt lgkmcnt(0)
	s_barrier
	s_setprio 1
	s_waitcnt lgkmcnt(0)
	v_mfma_f32_16x16x32_bf16 v[28:31], v[130:133], v[206:209], v[28:31]
	v_mfma_f32_16x16x32_bf16 v[24:27], v[182:185], v[206:209], v[24:27]
	v_mfma_f32_16x16x32_bf16 v[20:23], v[130:133], v[214:217], v[20:23]
	v_mfma_f32_16x16x32_bf16 v[16:19], v[182:185], v[214:217], v[16:19]
	v_mfma_f32_16x16x32_bf16 v[12:15], v[130:133], v[222:225], v[12:15]
	v_mfma_f32_16x16x32_bf16 v[8:11], v[182:185], v[222:225], v[8:11]
	v_mfma_f32_16x16x32_bf16 v[4:7], v[130:133], v[230:233], v[4:7]
	v_mfma_f32_16x16x32_bf16 v[0:3], v[182:185], v[230:233], v[0:3]
	v_mfma_f32_16x16x32_bf16 v[28:31], v[178:181], v[210:213], v[28:31]
	v_mfma_f32_16x16x32_bf16 v[24:27], v[186:189], v[210:213], v[24:27]
	v_mfma_f32_16x16x32_bf16 v[20:23], v[178:181], v[218:221], v[20:23]
	v_mfma_f32_16x16x32_bf16 v[16:19], v[186:189], v[218:221], v[16:19]
	v_mfma_f32_16x16x32_bf16 v[12:15], v[178:181], v[226:229], v[12:15]
	v_mfma_f32_16x16x32_bf16 v[8:11], v[186:189], v[226:229], v[8:11]
	v_mfma_f32_16x16x32_bf16 v[4:7], v[178:181], v[234:237], v[4:7]
	v_mfma_f32_16x16x32_bf16 v[0:3], v[186:189], v[234:237], v[0:3]
	s_setprio 0
	s_setprio 1
	v_mfma_f32_16x16x32_bf16 v[94:97], v[190:193], v[206:209], v[94:97]
	v_mfma_f32_16x16x32_bf16 v[90:93], v[198:201], v[206:209], v[90:93]
	v_mfma_f32_16x16x32_bf16 v[86:89], v[190:193], v[214:217], v[86:89]
	v_mfma_f32_16x16x32_bf16 v[82:85], v[198:201], v[214:217], v[82:85]
	v_mfma_f32_16x16x32_bf16 v[78:81], v[190:193], v[222:225], v[78:81]
	v_mfma_f32_16x16x32_bf16 v[70:73], v[198:201], v[222:225], v[70:73]
	v_mfma_f32_16x16x32_bf16 v[74:77], v[190:193], v[230:233], v[74:77]
	v_mfma_f32_16x16x32_bf16 v[64:67], v[198:201], v[230:233], v[66:69]
	v_mfma_f32_16x16x32_bf16 v[94:97], v[194:197], v[210:213], v[94:97]
	v_mfma_f32_16x16x32_bf16 v[90:93], v[202:205], v[210:213], v[90:93]
	v_mfma_f32_16x16x32_bf16 v[86:89], v[194:197], v[218:221], v[86:89]
	v_mfma_f32_16x16x32_bf16 v[82:85], v[202:205], v[218:221], v[82:85]
	v_mfma_f32_16x16x32_bf16 v[78:81], v[194:197], v[226:229], v[78:81]
	v_mfma_f32_16x16x32_bf16 v[70:73], v[202:205], v[226:229], v[70:73]
	v_mfma_f32_16x16x32_bf16 v[74:77], v[194:197], v[234:237], v[74:77]
	v_mfma_f32_16x16x32_bf16 v[64:67], v[202:205], v[234:237], v[64:67]
	s_setprio 0
	s_barrier
; #define PG8_STAGE(bufoff, gbase, voff) do { _Pragma("unroll") for (int _i = 0; _i < 2; ++_i) \
;         __builtin_amdgcn_global_load_lds((const unsigned*)((const char*)(gbase) + (voff)[_i]), (PG8_LAS unsigned*)(lds + (bufoff) + ldsw + _i * 8192), 16, 0, 0); } while (0)
; #define PG8_LDA(dst, b, h) do { _Pragma("unroll") for (int m = 0; m < 4; ++m) _Pragma("unroll") for (int k = 0; k < 2; ++k) dst[m][k] = *(const PG8_LAS bf16x8*)(lds + PG8_SA(b, h) + aoff + m * 2048 + k * 1024); } while (0)
; #define PG8_LDB(dst, b, h) do { _Pragma("unroll") for (int n = 0; n < 2; ++n) _Pragma("unroll") for (int k = 0; k < 2; ++k) dst[n][k] = *(const PG8_LAS bf16x8*)(lds + PG8_SB(b, h) + boff + n * 2048 + k * 1024); } while (0)
; #define PG8_MMA(ai, bj, At, Bt) do { __builtin_amdgcn_s_setprio(1); _Pragma("unroll") for (int m = 0; m < 4; ++m) _Pragma("unroll") for (int n = 0; n < 2; ++n) _Pragma("unroll") for (int k = 0; k < 2; ++k) \
;         acc[ai][bj][m][n] = __builtin_amdgcn_mfma_f32_16x16x32_bf16(Bt[n][k], At[m][k], acc[ai][bj][m][n], 0, 0, 0); __builtin_amdgcn_s_setprio(0); } while (0)
; #define PG8_WAIT_V(n) asm volatile("s_waitcnt vmcnt(" #n ")" ::: "memory")
; #define PG8_WAIT_L(n) asm volatile("s_waitcnt lgkmcnt(" #n ")" ::: "memory")
; #define PG8_BAR __builtin_amdgcn_s_barrier()
; #define PG8_SCHED __builtin_amdgcn_sched_barrier(0)
; template <class Epi, class Sched, bool ALIGN_EPI = false, bool SP2 = false>
; __device__ __forceinline__ void gemm_phase(PG8_LAS unsigned char* lds, const Gemm g, const Sched& S, const Epi& E) {
;     ...
;             PG8_LDB(B0, 1, 0); PG8_LDB(B1, 1, 1); PG8_SCHED; PG8_LDA(At, 1, 0); PG8_STAGE(PG8_SA(0, 1), a2 + hstep, voffA);
;             PG8_WAIT_V(8); PG8_WAIT_L(0); PG8_BAR; PG8_MMA(0, 0, At, B0); PG8_MMA(0, 1, At, B1); PG8_BAR; PG8_SCHED;
	s_add_i32 s35, 0, 0x18000
	v_add_u32_e32 v68, s35, v177
	s_add_i32 s56, 0, 0x1c000
	ds_read_b128 v[130:133], v68
	ds_read_b128 v[178:181], v68 offset:1024
	ds_read_b128 v[182:185], v68 offset:2048
	ds_read_b128 v[186:189], v68 offset:3072
	v_add_u32_e32 v68, s56, v244
	ds_read_b128 v[190:193], v68
	ds_read_b128 v[194:197], v68 offset:1024
	ds_read_b128 v[198:201], v68 offset:2048
	ds_read_b128 v[202:205], v68 offset:3072
	s_add_u32 s44, s44, 0x80000
	s_addc_u32 s45, s45, 0
	s_mov_b32 m0, s52
	v_lshl_add_u64 v[68:69], s[44:45], 0, v[134:135]
	ds_read_b128 v[206:209], v176 offset:32768
	ds_read_b128 v[210:213], v176 offset:33792
	ds_read_b128 v[214:217], v176 offset:34816
	ds_read_b128 v[218:221], v176 offset:35840
	ds_read_b128 v[222:225], v176 offset:36864
	ds_read_b128 v[226:229], v176 offset:37888
	ds_read_b128 v[230:233], v176 offset:38912
	ds_read_b128 v[234:237], v176 offset:39936
	global_load_lds_dwordx4 v[68:69], off
	v_lshl_add_u64 v[68:69], s[44:45], 0, v[138:139]
	s_mov_b32 m0, s53
	s_nop 0
	global_load_lds_dwordx4 v[68:69], off
	s_waitcnt vmcnt(8)
	s_waitcnt lgkmcnt(0)
	s_barrier
	s_setprio 1
	s_waitcnt lgkmcnt(0)
	v_mfma_f32_16x16x32_bf16 v[60:63], v[130:133], v[206:209], v[60:63]
	v_mfma_f32_16x16x32_bf16 v[56:59], v[182:185], v[206:209], v[56:59]
	v_mfma_f32_16x16x32_bf16 v[52:55], v[130:133], v[214:217], v[52:55]
	v_mfma_f32_16x16x32_bf16 v[48:51], v[182:185], v[214:217], v[48:51]
	v_mfma_f32_16x16x32_bf16 v[44:47], v[130:133], v[222:225], v[44:47]
	v_mfma_f32_16x16x32_bf16 v[40:43], v[182:185], v[222:225], v[40:43]
	v_mfma_f32_16x16x32_bf16 v[36:39], v[130:133], v[230:233], v[36:39]
	v_mfma_f32_16x16x32_bf16 v[32:35], v[182:185], v[230:233], v[32:35]
	v_mfma_f32_16x16x32_bf16 v[60:63], v[178:181], v[210:213], v[60:63]
	v_mfma_f32_16x16x32_bf16 v[56:59], v[186:189], v[210:213], v[56:59]
	v_mfma_f32_16x16x32_bf16 v[52:55], v[178:181], v[218:221], v[52:55]
	v_mfma_f32_16x16x32_bf16 v[48:51], v[186:189], v[218:221], v[48:51]
	v_mfma_f32_16x16x32_bf16 v[44:47], v[178:181], v[226:229], v[44:47]
	v_mfma_f32_16x16x32_bf16 v[40:43], v[186:189], v[226:229], v[40:43]
	v_mfma_f32_16x16x32_bf16 v[36:39], v[178:181], v[234:237], v[36:39]
	v_mfma_f32_16x16x32_bf16 v[32:35], v[186:189], v[234:237], v[32:35]
	s_setprio 0
	s_setprio 1
	v_mfma_f32_16x16x32_bf16 v[126:129], v[190:193], v[206:209], v[126:129]
	v_mfma_f32_16x16x32_bf16 v[122:125], v[198:201], v[206:209], v[122:125]
	v_mfma_f32_16x16x32_bf16 v[118:121], v[190:193], v[214:217], v[118:121]
	v_mfma_f32_16x16x32_bf16 v[114:117], v[198:201], v[214:217], v[114:117]
	v_mfma_f32_16x16x32_bf16 v[110:113], v[190:193], v[222:225], v[110:113]
	v_mfma_f32_16x16x32_bf16 v[106:109], v[198:201], v[222:225], v[106:109]
	v_mfma_f32_16x16x32_bf16 v[102:105], v[190:193], v[230:233], v[102:105]
	v_mfma_f32_16x16x32_bf16 v[98:101], v[198:201], v[230:233], v[98:101]
	v_mfma_f32_16x16x32_bf16 v[126:129], v[194:197], v[210:213], v[126:129]
	v_mfma_f32_16x16x32_bf16 v[122:125], v[202:205], v[210:213], v[122:125]
	v_mfma_f32_16x16x32_bf16 v[118:121], v[194:197], v[218:221], v[118:121]
	v_mfma_f32_16x16x32_bf16 v[114:117], v[202:205], v[218:221], v[114:117]
	v_mfma_f32_16x16x32_bf16 v[110:113], v[194:197], v[226:229], v[110:113]
	v_mfma_f32_16x16x32_bf16 v[106:109], v[202:205], v[226:229], v[106:109]
	v_mfma_f32_16x16x32_bf16 v[102:105], v[194:197], v[234:237], v[102:105]
	v_mfma_f32_16x16x32_bf16 v[98:101], v[202:205], v[234:237], v[98:101]
	s_setprio 0
	s_barrier
; #define PG8_STAGE(bufoff, gbase, voff) do { _Pragma("unroll") for (int _i = 0; _i < 2; ++_i) \
;         __builtin_amdgcn_global_load_lds((const unsigned*)((const char*)(gbase) + (voff)[_i]), (PG8_LAS unsigned*)(lds + (bufoff) + ldsw + _i * 8192), 16, 0, 0); } while (0)
; #define PG8_LDA(dst, b, h) do { _Pragma("unroll") for (int m = 0; m < 4; ++m) _Pragma("unroll") for (int k = 0; k < 2; ++k) dst[m][k] = *(const PG8_LAS bf16x8*)(lds + PG8_SA(b, h) + aoff + m * 2048 + k * 1024); } while (0)
; #define PG8_MMA(ai, bj, At, Bt) do { __builtin_amdgcn_s_setprio(1); _Pragma("unroll") for (int m = 0; m < 4; ++m) _Pragma("unroll") for (int n = 0; n < 2; ++n) _Pragma("unroll") for (int k = 0; k < 2; ++k) \
;         acc[ai][bj][m][n] = __builtin_amdgcn_mfma_f32_16x16x32_bf16(Bt[n][k], At[m][k], acc[ai][bj][m][n], 0, 0, 0); __builtin_amdgcn_s_setprio(0); } while (0)
; #define PG8_WAIT_V(n) asm volatile("s_waitcnt vmcnt(" #n ")" ::: "memory")
; #define PG8_WAIT_L(n) asm volatile("s_waitcnt lgkmcnt(" #n ")" ::: "memory")
; #define PG8_BAR __builtin_amdgcn_s_barrier()
; #define PG8_SCHED __builtin_amdgcn_sched_barrier(0)
; template <class Epi, class Sched, bool ALIGN_EPI = false, bool SP2 = false>
; __device__ __forceinline__ void gemm_phase(PG8_LAS unsigned char* lds, const Gemm g, const Sched& S, const Epi& E) {
;     ...
;         for (int t = 0; t < nt; t += 2) {
;     ...
;             PG8_LDA(At, 1, 1); PG8_STAGE(PG8_SB(1, 0), b3, voffB); PG8_STAGE(PG8_SB(1, 1), b3 + hstep, voffB); PG8_STAGE(PG8_SA(1, 0), a3, voffA);
;             PG8_WAIT_V(8); PG8_WAIT_L(0); PG8_BAR; PG8_MMA(1, 0, At, B0); PG8_MMA(1, 1, At, B1); PG8_BAR; PG8_SCHED;
	s_add_i32 s35, s35, s49
	v_lshl_add_u64 v[68:69], v[156:157], 0, s[16:17]
	s_mov_b32 m0, s35
	ds_read_b128 v[206:209], v176 offset:49152
	ds_read_b128 v[210:213], v176 offset:50176
	ds_read_b128 v[214:217], v176 offset:51200
	ds_read_b128 v[218:221], v176 offset:52224
	ds_read_b128 v[222:225], v176 offset:53248
	ds_read_b128 v[226:229], v176 offset:54272
	ds_read_b128 v[230:233], v176 offset:55296
	ds_read_b128 v[234:237], v176 offset:56320
	global_load_lds_dwordx4 v[68:69], off
	s_add_i32 m0, s35, 0x2000
	s_add_u32 s42, s42, 0x80080
	v_lshl_add_u64 v[68:69], v[238:239], 0, s[16:17]
	s_addc_u32 s43, s43, 0
	s_add_i32 s35, s56, s49
	global_load_lds_dwordx4 v[68:69], off
	v_lshl_add_u64 v[68:69], s[42:43], 0, v[136:137]
	s_mov_b32 m0, s35
	s_nop 0
	global_load_lds_dwordx4 v[68:69], off
	v_lshl_add_u64 v[68:69], s[42:43], 0, v[140:141]
	s_add_i32 m0, s35, 0x2000
	s_nop 0
	global_load_lds_dwordx4 v[68:69], off
	v_lshl_add_u64 v[68:69], v[240:241], 0, s[16:17]
	s_mov_b32 m0, s67
	s_nop 0
	global_load_lds_dwordx4 v[68:69], off
	v_lshl_add_u64 v[68:69], v[242:243], 0, s[16:17]
	s_mov_b32 m0, s68
	s_nop 0
	global_load_lds_dwordx4 v[68:69], off
	s_waitcnt vmcnt(8)
	s_waitcnt lgkmcnt(0)
	s_barrier
	s_setprio 1
	s_waitcnt lgkmcnt(0)
	v_mfma_f32_16x16x32_bf16 v[28:31], v[130:133], v[206:209], v[28:31]
	v_mfma_f32_16x16x32_bf16 v[24:27], v[182:185], v[206:209], v[24:27]
	v_mfma_f32_16x16x32_bf16 v[20:23], v[130:133], v[214:217], v[20:23]
	v_mfma_f32_16x16x32_bf16 v[16:19], v[182:185], v[214:217], v[16:19]
	v_mfma_f32_16x16x32_bf16 v[12:15], v[130:133], v[222:225], v[12:15]
	v_mfma_f32_16x16x32_bf16 v[8:11], v[182:185], v[222:225], v[8:11]
	v_mfma_f32_16x16x32_bf16 v[4:7], v[130:133], v[230:233], v[4:7]
	v_mfma_f32_16x16x32_bf16 v[0:3], v[182:185], v[230:233], v[0:3]
	v_mfma_f32_16x16x32_bf16 v[28:31], v[178:181], v[210:213], v[28:31]
	v_mfma_f32_16x16x32_bf16 v[24:27], v[186:189], v[210:213], v[24:27]
	v_mfma_f32_16x16x32_bf16 v[20:23], v[178:181], v[218:221], v[20:23]
	v_mfma_f32_16x16x32_bf16 v[16:19], v[186:189], v[218:221], v[16:19]
	v_mfma_f32_16x16x32_bf16 v[12:15], v[178:181], v[226:229], v[12:15]
	v_mfma_f32_16x16x32_bf16 v[8:11], v[186:189], v[226:229], v[8:11]
	v_mfma_f32_16x16x32_bf16 v[4:7], v[178:181], v[234:237], v[4:7]
	v_mfma_f32_16x16x32_bf16 v[0:3], v[186:189], v[234:237], v[0:3]
	s_setprio 0
	s_setprio 1
	v_mfma_f32_16x16x32_bf16 v[94:97], v[190:193], v[206:209], v[94:97]
	v_mfma_f32_16x16x32_bf16 v[90:93], v[198:201], v[206:209], v[90:93]
	v_mfma_f32_16x16x32_bf16 v[86:89], v[190:193], v[214:217], v[86:89]
	v_mfma_f32_16x16x32_bf16 v[82:85], v[198:201], v[214:217], v[82:85]
	v_mfma_f32_16x16x32_bf16 v[78:81], v[190:193], v[222:225], v[78:81]
	v_mfma_f32_16x16x32_bf16 v[68:71], v[198:201], v[222:225], v[70:73]
	v_mfma_f32_16x16x32_bf16 v[74:77], v[190:193], v[230:233], v[74:77]
	v_mfma_f32_16x16x32_bf16 v[64:67], v[198:201], v[230:233], v[64:67]
	v_mfma_f32_16x16x32_bf16 v[94:97], v[194:197], v[210:213], v[94:97]
	v_mfma_f32_16x16x32_bf16 v[90:93], v[202:205], v[210:213], v[90:93]
	v_mfma_f32_16x16x32_bf16 v[86:89], v[194:197], v[218:221], v[86:89]
	v_mfma_f32_16x16x32_bf16 v[82:85], v[202:205], v[218:221], v[82:85]
	v_mfma_f32_16x16x32_bf16 v[78:81], v[194:197], v[226:229], v[78:81]
	v_mfma_f32_16x16x32_bf16 v[70:73], v[202:205], v[226:229], v[68:71]
	v_mfma_f32_16x16x32_bf16 v[74:77], v[194:197], v[234:237], v[74:77]
	v_mfma_f32_16x16x32_bf16 v[66:69], v[202:205], v[234:237], v[64:67]
	s_setprio 0
	s_barrier
	s_add_i32 s33, s33, 2
	s_add_u32 s40, s40, 0x100
	s_addc_u32 s41, s41, 0
	s_add_u32 s13, s13, 0x100
	s_addc_u32 s31, s31, 0
	s_cmp_gt_u32 s33, 29
	s_cbranch_scc0 .LBB0_188
	s_and_b64 vcc, exec, s[18:19]
	s_cbranch_vccz .LBB0_191
	s_barrier

; __device__ __forceinline__ unsigned pk2(float lo, float hi) { const f32x2 v = {lo, hi}; const bf16x2_t b = __builtin_convertvector(v, bf16x2_t); return __builtin_bit_cast(unsigned, b); }
;     __device__ __forceinline__ void operator()(const f32x4 (&acc)[2][2][4][2], const pg8::Unit& u, int wr, int wc, int fr, int fq) const {
;     ...
;             bf16_t* O = (bf16_t*)base; const int col0 = colt + wc * 32 + 8 * fq;
; #pragma unroll
;             for (int ai = 0; ai < 2; ++ai)
; #pragma unroll
;                 for (int m = 0; m < 4; ++m) { bf16_t* rowp = O + (size_t)(row0 + ai * 128 + m * 16) * ld + col0;
; #pragma unroll
;                     for (int bj = 0; bj < 2; ++bj) { const f32x4 v0 = acc[ai][bj][m][0], v1 = acc[ai][bj][m][1];
;                         u32x4 w; w.x = pk2(v0[0], v0[1]); w.y = pk2(v0[2], v0[3]); w.z = pk2(v1[0], v1[1]); w.w = pk2(v1[2], v1[3]);
;                         *(u32x4*)(rowp + bj * 128) = w; } }
.LBB0_197:
	s_and_b32 s7, s6, -4
	s_cmp_lg_u32 s7, 8
	s_cselect_b64 s[44:45], -1, 0
	s_and_b32 s7, s6, -8
	s_cmp_lg_u32 s7, 24
	s_cselect_b64 s[56:57], -1, 0
	s_and_b64 s[56:57], s[44:45], s[56:57]
	s_lshl_b32 s7, s6, 8
	s_and_b32 s10, s3, s7
	s_mov_b64 s[44:45], -1
	s_and_b64 vcc, exec, s[56:57]
	v_cvt_pk_bf16_f32 v130, v60, v61
	v_cvt_pk_bf16_f32 v131, v62, v63
	v_cvt_pk_bf16_f32 v132, v56, v57
	v_cvt_pk_bf16_f32 v133, v58, v59
	v_cvt_pk_bf16_f32 v126, v126, v127
	v_cvt_pk_bf16_f32 v127, v128, v129
	v_cvt_pk_bf16_f32 v128, v122, v123
	v_cvt_pk_bf16_f32 v129, v124, v125
	v_cvt_pk_bf16_f32 v122, v52, v53
	v_cvt_pk_bf16_f32 v123, v54, v55
	v_cvt_pk_bf16_f32 v124, v48, v49
	v_cvt_pk_bf16_f32 v125, v50, v51
	v_cvt_pk_bf16_f32 v118, v118, v119
	v_cvt_pk_bf16_f32 v119, v120, v121
	v_cvt_pk_bf16_f32 v120, v114, v115
	v_cvt_pk_bf16_f32 v121, v116, v117
	v_cvt_pk_bf16_f32 v114, v44, v45
	v_cvt_pk_bf16_f32 v115, v46, v47
	v_cvt_pk_bf16_f32 v116, v40, v41
	v_cvt_pk_bf16_f32 v117, v42, v43
	v_cvt_pk_bf16_f32 v110, v110, v111
	v_cvt_pk_bf16_f32 v111, v112, v113
	v_cvt_pk_bf16_f32 v112, v106, v107
	v_cvt_pk_bf16_f32 v113, v108, v109
	v_cvt_pk_bf16_f32 v106, v36, v37
	v_cvt_pk_bf16_f32 v107, v38, v39
	v_cvt_pk_bf16_f32 v108, v32, v33
	v_cvt_pk_bf16_f32 v109, v34, v35
	v_cvt_pk_bf16_f32 v102, v102, v103
	v_cvt_pk_bf16_f32 v103, v104, v105
	v_cvt_pk_bf16_f32 v104, v98, v99
	v_cvt_pk_bf16_f32 v105, v100, v101
	v_cvt_pk_bf16_f32 v98, v28, v29
	v_cvt_pk_bf16_f32 v99, v30, v31
	v_cvt_pk_bf16_f32 v100, v24, v25
	v_cvt_pk_bf16_f32 v101, v26, v27
	v_cvt_pk_bf16_f32 v94, v94, v95
	v_cvt_pk_bf16_f32 v95, v96, v97
	v_cvt_pk_bf16_f32 v96, v90, v91
	v_cvt_pk_bf16_f32 v97, v92, v93
	v_cvt_pk_bf16_f32 v90, v20, v21
	v_cvt_pk_bf16_f32 v91, v22, v23
	v_cvt_pk_bf16_f32 v92, v16, v17
	v_cvt_pk_bf16_f32 v93, v18, v19
	v_cvt_pk_bf16_f32 v86, v86, v87
	v_cvt_pk_bf16_f32 v87, v88, v89
	v_cvt_pk_bf16_f32 v88, v82, v83
	v_cvt_pk_bf16_f32 v89, v84, v85
	v_cvt_pk_bf16_f32 v82, v12, v13
	v_cvt_pk_bf16_f32 v83, v14, v15
	v_cvt_pk_bf16_f32 v84, v8, v9
	v_cvt_pk_bf16_f32 v85, v10, v11
	v_cvt_pk_bf16_f32 v78, v78, v79
	v_cvt_pk_bf16_f32 v79, v80, v81
	v_cvt_pk_bf16_f32 v80, v70, v71
	v_cvt_pk_bf16_f32 v81, v72, v73
	v_cvt_pk_bf16_f32 v70, v4, v5
	v_cvt_pk_bf16_f32 v71, v6, v7
	v_cvt_pk_bf16_f32 v72, v0, v1
	v_cvt_pk_bf16_f32 v73, v2, v3
	v_cvt_pk_bf16_f32 v64, v74, v75
	v_cvt_pk_bf16_f32 v65, v76, v77
	v_cvt_pk_bf16_f32 v66, v66, v67
	v_cvt_pk_bf16_f32 v67, v68, v69
	s_cbranch_vccz .LBB0_199
	s_and_b32 s32, s0, 3
	s_lshl_b32 s32, s32, 5
	v_add_u32_e32 v68, s32, v162
	v_or_b32_e32 v68, s10, v68
	v_lshlrev_b32_e32 v142, 1, v68
	v_lshl_add_u64 v[68:69], s[40:41], 0, v[142:143]
	v_mad_i64_i32 v[74:75], s[44:45], s42, v156, 0
	v_lshl_add_u64 v[74:75], v[74:75], 1, v[68:69]
	global_store_dwordx4 v[74:75], v[130:133], off nt
	global_store_dwordx4 v[74:75], v[126:129], off offset:64 nt
	v_or_b32_e32 v74, 16, v156
	v_mad_i64_i32 v[74:75], s[44:45], s42, v74, 0
	v_lshl_add_u64 v[74:75], v[74:75], 1, v[68:69]
	global_store_dwordx4 v[74:75], v[122:125], off nt
	global_store_dwordx4 v[74:75], v[118:121], off offset:64 nt
	v_or_b32_e32 v74, 32, v156
	v_mad_i64_i32 v[74:75], s[44:45], s42, v74, 0
	v_lshl_add_u64 v[74:75], v[74:75], 1, v[68:69]
	global_store_dwordx4 v[74:75], v[114:117], off nt
	global_store_dwordx4 v[74:75], v[110:113], off offset:64 nt
	v_or_b32_e32 v74, 48, v156
	v_mad_i64_i32 v[74:75], s[44:45], s42, v74, 0
	v_lshl_add_u64 v[74:75], v[74:75], 1, v[68:69]
	global_store_dwordx4 v[74:75], v[106:109], off nt
	global_store_dwordx4 v[74:75], v[102:105], off offset:64 nt
	v_add_u32_e32 v74, 0x80, v156
	v_mad_i64_i32 v[74:75], s[44:45], s42, v74, 0
	v_lshl_add_u64 v[74:75], v[74:75], 1, v[68:69]
	global_store_dwordx4 v[74:75], v[98:101], off nt
	global_store_dwordx4 v[74:75], v[94:97], off offset:64 nt
	v_add_u32_e32 v74, 0x90, v156
	v_mad_i64_i32 v[74:75], s[44:45], s42, v74, 0
	v_lshl_add_u64 v[74:75], v[74:75], 1, v[68:69]
	global_store_dwordx4 v[74:75], v[90:93], off nt
	global_store_dwordx4 v[74:75], v[86:89], off offset:64 nt
	v_add_u32_e32 v74, 0xa0, v156
	v_mad_i64_i32 v[74:75], s[44:45], s42, v74, 0
	v_lshl_add_u64 v[74:75], v[74:75], 1, v[68:69]
	global_store_dwordx4 v[74:75], v[82:85], off nt
	global_store_dwordx4 v[74:75], v[78:81], off offset:64 nt
	v_add_u32_e32 v74, 0xb0, v156
	v_mad_i64_i32 v[74:75], s[42:43], s42, v74, 0
	v_lshl_add_u64 v[68:69], v[74:75], 1, v[68:69]
	global_store_dwordx4 v[68:69], v[70:73], off nt
	global_store_dwordx4 v[68:69], v[64:67], off offset:64 nt
	s_mov_b64 s[44:45], 0
